# attention epilogue: all eight gain vectors loaded up front so the output stores pipeline instead of store-load-wait x7
# speedup vs baseline: 1.0026x; 1.0026x over previous
.LBB0_691:
	ds_bpermute_b32 v3, v35, v2
	s_mov_b32 s40, 0
	s_waitcnt lgkmcnt(0)
	v_add_f32_e32 v2, v2, v3
	ds_bpermute_b32 v3, v149, v2
	s_waitcnt lgkmcnt(0)
	v_add_f32_e32 v2, v2, v3
	ds_bpermute_b32 v3, v35, v132
	s_waitcnt lgkmcnt(0)
	v_add_f32_e32 v3, v132, v3
	ds_bpermute_b32 v4, v149, v3
	s_waitcnt lgkmcnt(0)
	v_add_f32_e32 v3, v3, v4
	v_div_scale_f32 v4, s[2:3], v2, v2, 1.0
	v_rcp_f32_e32 v5, v4
	s_nop 0
	v_fma_f32 v6, -v4, v5, 1.0
	v_fmac_f32_e32 v5, v6, v5
	v_div_scale_f32 v6, vcc, 1.0, v2, 1.0
	v_mul_f32_e32 v7, v6, v5
	v_fma_f32 v8, -v4, v7, v6
	v_fmac_f32_e32 v7, v8, v5
	v_fma_f32 v4, -v4, v7, v6
	v_div_fmas_f32 v4, v4, v5, v7
	v_div_fixup_f32 v12, v4, v2, 1.0
	v_div_scale_f32 v2, s[2:3], v3, v3, v181
	v_rcp_f32_e32 v4, v2
	s_nop 0
	v_fma_f32 v5, -v2, v4, 1.0
	v_fmac_f32_e32 v4, v5, v4
	v_div_scale_f32 v5, vcc, v181, v3, v181
	v_mul_f32_e32 v6, v5, v4
	v_fma_f32 v7, -v2, v6, v5
	v_fmac_f32_e32 v6, v7, v4
	v_fma_f32 v2, -v2, v6, v5
	v_div_fmas_f32 v2, v2, v4, v6
	v_div_fixup_f32 v14, v2, v3, v181
	v_pk_mul_f32 v[8:9], v[126:127], v[14:15] op_sel_hi:[1,0]
	v_pk_mul_f32 v[24:25], v[124:125], v[14:15] op_sel_hi:[1,0]
	v_pk_fma_f32 v[20:21], v[90:91], v[12:13], v[8:9] op_sel_hi:[1,0,1] neg_lo:[0,0,1] neg_hi:[0,0,1]
	global_load_dwordx4 v[8:11], v[160:161], off
	global_load_dwordx4 v[80:83], v[160:161], off offset:64
	global_load_dwordx4 v[84:87], v[160:161], off offset:128
	global_load_dwordx4 v[92:95], v[160:161], off offset:192
	global_load_dwordx4 v[228:231], v[160:161], off offset:256
	global_load_dwordx4 v[232:235], v[160:161], off offset:320
	global_load_dwordx4 v[236:239], v[160:161], off offset:384
	global_load_dwordx4 v[240:243], v[160:161], off offset:448
	v_pk_fma_f32 v[24:25], v[88:89], v[12:13], v[24:25] op_sel_hi:[1,0,1] neg_lo:[0,0,1] neg_hi:[0,0,1]
	v_pk_mul_f32 v[22:23], v[20:21], v[20:21]
	v_pk_mul_f32 v[26:27], v[24:25], v[24:25]
	v_pk_mul_f32 v[32:33], v[120:121], v[14:15] op_sel_hi:[1,0]
	v_add_f32_e32 v26, v26, v27
	v_pk_fma_f32 v[32:33], v[76:77], v[12:13], v[32:33] op_sel_hi:[1,0,1] neg_lo:[0,0,1] neg_hi:[0,0,1]
	v_add_f32_e32 v22, v22, v26
	v_pk_mul_f32 v[28:29], v[122:123], v[14:15] op_sel_hi:[1,0]
	v_pk_mul_f32 v[36:37], v[32:33], v[32:33]
	v_add_f32_e32 v22, v23, v22
	v_pk_fma_f32 v[28:29], v[78:79], v[12:13], v[28:29] op_sel_hi:[1,0,1] neg_lo:[0,0,1] neg_hi:[0,0,1]
	v_add_f32_e32 v22, v36, v22
	v_pk_mul_f32 v[30:31], v[28:29], v[28:29]
	v_pk_mul_f32 v[42:43], v[116:117], v[14:15] op_sel_hi:[1,0]
	v_add_f32_e32 v22, v37, v22
	v_pk_fma_f32 v[42:43], v[68:69], v[12:13], v[42:43] op_sel_hi:[1,0,1] neg_lo:[0,0,1] neg_hi:[0,0,1]
	v_add_f32_e32 v22, v30, v22
	v_pk_mul_f32 v[38:39], v[118:119], v[14:15] op_sel_hi:[1,0]
	v_pk_mul_f32 v[44:45], v[42:43], v[42:43]
	v_add_f32_e32 v22, v31, v22
	v_pk_fma_f32 v[38:39], v[70:71], v[12:13], v[38:39] op_sel_hi:[1,0,1] neg_lo:[0,0,1] neg_hi:[0,0,1]
	v_add_f32_e32 v22, v44, v22
	v_pk_mul_f32 v[40:41], v[38:39], v[38:39]
	v_pk_mul_f32 v[50:51], v[112:113], v[14:15] op_sel_hi:[1,0]
	v_add_f32_e32 v22, v45, v22
	v_pk_fma_f32 v[50:51], v[64:65], v[12:13], v[50:51] op_sel_hi:[1,0,1] neg_lo:[0,0,1] neg_hi:[0,0,1]
	v_add_f32_e32 v22, v40, v22
	v_pk_mul_f32 v[46:47], v[114:115], v[14:15] op_sel_hi:[1,0]
	v_pk_mul_f32 v[64:65], v[50:51], v[50:51]
	v_add_f32_e32 v22, v41, v22
	v_pk_fma_f32 v[46:47], v[66:67], v[12:13], v[46:47] op_sel_hi:[1,0,1] neg_lo:[0,0,1] neg_hi:[0,0,1]
	v_add_f32_e32 v22, v64, v22
	v_pk_mul_f32 v[48:49], v[46:47], v[46:47]
	v_pk_mul_f32 v[68:69], v[108:109], v[14:15] op_sel_hi:[1,0]
	v_add_f32_e32 v22, v65, v22
	v_pk_fma_f32 v[60:61], v[60:61], v[12:13], v[68:69] op_sel_hi:[1,0,1] neg_lo:[0,0,1] neg_hi:[0,0,1]
	v_add_f32_e32 v22, v48, v22
	v_pk_mul_f32 v[66:67], v[110:111], v[14:15] op_sel_hi:[1,0]
	v_pk_mul_f32 v[68:69], v[60:61], v[60:61]
	v_add_f32_e32 v22, v49, v22
	v_pk_fma_f32 v[62:63], v[62:63], v[12:13], v[66:67] op_sel_hi:[1,0,1] neg_lo:[0,0,1] neg_hi:[0,0,1]
	v_add_f32_e32 v22, v68, v22
	v_pk_mul_f32 v[66:67], v[62:63], v[62:63]
	s_waitcnt vmcnt(4)
	v_pk_mul_f32 v[72:73], v[104:105], v[14:15] op_sel_hi:[1,0]
	v_add_f32_e32 v22, v69, v22
	v_pk_fma_f32 v[56:57], v[56:57], v[12:13], v[72:73] op_sel_hi:[1,0,1] neg_lo:[0,0,1] neg_hi:[0,0,1]
	v_add_f32_e32 v22, v66, v22
	v_pk_mul_f32 v[70:71], v[106:107], v[14:15] op_sel_hi:[1,0]
	v_pk_mul_f32 v[72:73], v[56:57], v[56:57]
	v_add_f32_e32 v22, v67, v22
	v_pk_mul_f32 v[2:3], v[128:129], v[14:15] op_sel_hi:[1,0]
	v_pk_fma_f32 v[58:59], v[58:59], v[12:13], v[70:71] op_sel_hi:[1,0,1] neg_lo:[0,0,1] neg_hi:[0,0,1]
	v_add_f32_e32 v22, v72, v22
	v_pk_fma_f32 v[6:7], v[96:97], v[12:13], v[2:3] op_sel_hi:[1,0,1] neg_lo:[0,0,1] neg_hi:[0,0,1]
	v_pk_mul_f32 v[2:3], v[130:131], v[14:15] op_sel_hi:[1,0]
	v_pk_mul_f32 v[70:71], v[58:59], v[58:59]
	v_pk_mul_f32 v[74:75], v[102:103], v[14:15] op_sel_hi:[1,0]
	v_pk_mul_f32 v[14:15], v[100:101], v[14:15] op_sel_hi:[1,0]
	v_add_f32_e32 v22, v73, v22
	v_pk_fma_f32 v[4:5], v[98:99], v[12:13], v[2:3] op_sel_hi:[1,0,1] neg_lo:[0,0,1] neg_hi:[0,0,1]
	v_pk_fma_f32 v[54:55], v[54:55], v[12:13], v[74:75] op_sel_hi:[1,0,1] neg_lo:[0,0,1] neg_hi:[0,0,1]
	v_pk_fma_f32 v[12:13], v[52:53], v[12:13], v[14:15] op_sel_hi:[1,0,1] neg_lo:[0,0,1] neg_hi:[0,0,1]
	v_add_f32_e32 v22, v70, v22
	v_pk_mul_f32 v[14:15], v[12:13], v[12:13]
	v_add_f32_e32 v22, v71, v22
	v_add_f32_e32 v14, v14, v22
	v_pk_mul_f32 v[74:75], v[54:55], v[54:55]
	v_add_f32_e32 v14, v15, v14
	v_add_f32_e32 v14, v74, v14
	v_pk_mul_f32 v[16:17], v[6:7], v[6:7]
	v_add_f32_e32 v14, v75, v14
	v_add_f32_e32 v14, v16, v14
	v_pk_mul_f32 v[18:19], v[4:5], v[4:5]
	v_add_f32_e32 v14, v17, v14
	v_add_f32_e32 v14, v18, v14
	v_add_f32_e32 v14, v19, v14
	ds_bpermute_b32 v15, v35, v14
	v_lshlrev_b32_e32 v2, 1, v156
	v_mov_b32_e32 v3, v34
	v_lshl_add_u64 v[2:3], v[168:169], 0, v[2:3]
	s_waitcnt lgkmcnt(0)
	v_add_f32_e32 v14, v14, v15
	ds_bpermute_b32 v15, v149, v14
	s_waitcnt lgkmcnt(0)
	v_add_f32_e32 v14, v14, v15
	v_fmamk_f32 v14, v14, 0x3c000000, v212
	v_cmp_gt_f32_e32 vcc, s27, v14
	v_mul_f32_e32 v15, 0x4b800000, v14
	s_nop 0
	v_cndmask_b32_e32 v14, v14, v15, vcc
	v_rsq_f32_e32 v14, v14
	s_nop 0
	v_mul_f32_e32 v15, 0x45800000, v14
	v_cndmask_b32_e32 v14, v14, v15, vcc
	v_mul_f32_e32 v14, v179, v14
	v_pk_mul_f32 v[16:17], v[24:25], v[14:15] op_sel_hi:[1,0]
	v_pk_mul_f32 v[12:13], v[12:13], v[14:15] op_sel_hi:[1,0]
	s_waitcnt vmcnt(0)
	v_pk_mul_f32 v[8:9], v[8:9], v[16:17]
	v_pk_mul_f32 v[16:17], v[20:21], v[14:15] op_sel_hi:[1,0]
	v_cvt_pk_f16_f32 v8, v8, v9
	v_pk_mul_f32 v[10:11], v[10:11], v[16:17]
	v_pk_mul_f32 v[16:17], v[32:33], v[14:15] op_sel_hi:[1,0]
	v_cvt_pk_f16_f32 v9, v10, v11
	global_store_dwordx2 v[2:3], v[8:9], off offset:1024
	v_pk_mul_f32 v[6:7], v[6:7], v[14:15] op_sel_hi:[1,0]
	v_pk_mul_f32 v[4:5], v[4:5], v[14:15] op_sel_hi:[1,0]
	v_pk_mul_f32 v[8:9], v[80:81], v[16:17]
	v_pk_mul_f32 v[16:17], v[28:29], v[14:15] op_sel_hi:[1,0]
	v_cvt_pk_f16_f32 v8, v8, v9
	v_pk_mul_f32 v[10:11], v[82:83], v[16:17]
	v_pk_mul_f32 v[16:17], v[42:43], v[14:15] op_sel_hi:[1,0]
	v_cvt_pk_f16_f32 v9, v10, v11
	global_store_dwordx2 v[2:3], v[8:9], off offset:1056
	v_pk_mul_f32 v[8:9], v[84:85], v[16:17]
	v_pk_mul_f32 v[16:17], v[38:39], v[14:15] op_sel_hi:[1,0]
	v_cvt_pk_f16_f32 v8, v8, v9
	v_pk_mul_f32 v[10:11], v[86:87], v[16:17]
	v_pk_mul_f32 v[16:17], v[50:51], v[14:15] op_sel_hi:[1,0]
	v_cvt_pk_f16_f32 v9, v10, v11
	global_store_dwordx2 v[2:3], v[8:9], off offset:1088
	v_pk_mul_f32 v[8:9], v[92:93], v[16:17]
	v_pk_mul_f32 v[16:17], v[46:47], v[14:15] op_sel_hi:[1,0]
	v_cvt_pk_f16_f32 v8, v8, v9
	v_pk_mul_f32 v[10:11], v[94:95], v[16:17]
	v_pk_mul_f32 v[16:17], v[60:61], v[14:15] op_sel_hi:[1,0]
	v_cvt_pk_f16_f32 v9, v10, v11
	global_store_dwordx2 v[2:3], v[8:9], off offset:1120
	v_pk_mul_f32 v[8:9], v[228:229], v[16:17]
	v_pk_mul_f32 v[16:17], v[62:63], v[14:15] op_sel_hi:[1,0]
	v_cvt_pk_f16_f32 v8, v8, v9
	v_pk_mul_f32 v[10:11], v[230:231], v[16:17]
	v_pk_mul_f32 v[16:17], v[56:57], v[14:15] op_sel_hi:[1,0]
	v_cvt_pk_f16_f32 v9, v10, v11
	global_store_dwordx2 v[2:3], v[8:9], off offset:1152
	v_pk_mul_f32 v[8:9], v[232:233], v[16:17]
	v_pk_mul_f32 v[16:17], v[58:59], v[14:15] op_sel_hi:[1,0]
	v_cvt_pk_f16_f32 v8, v8, v9
	v_pk_mul_f32 v[10:11], v[234:235], v[16:17]
	s_nop 0
	v_cvt_pk_f16_f32 v9, v10, v11
	global_store_dwordx2 v[2:3], v[8:9], off offset:1184
	v_pk_mul_f32 v[8:9], v[236:237], v[12:13]
	v_pk_mul_f32 v[12:13], v[54:55], v[14:15] op_sel_hi:[1,0]
	v_cvt_pk_f16_f32 v8, v8, v9
	v_pk_mul_f32 v[10:11], v[238:239], v[12:13]
	s_nop 0
	v_cvt_pk_f16_f32 v9, v10, v11
	global_store_dwordx2 v[2:3], v[8:9], off offset:1216
	v_pk_mul_f32 v[6:7], v[240:241], v[6:7]
	v_pk_mul_f32 v[4:5], v[242:243], v[4:5]
	v_cvt_pk_f16_f32 v6, v6, v7
	v_cvt_pk_f16_f32 v7, v4, v5
	global_store_dwordx2 v[2:3], v[6:7], off offset:1248
